# attention: cross-half row-max exchange via v_permlane32_swap instead of a ds_bpermute LDS round trip
# speedup vs baseline: 1.0031x; 1.0031x over previous
.LBB0_323:
	s_nop 10
	v_max3_f32 v0, v80, s18, v81
	v_max3_f32 v0, v0, v82, v83
	v_max3_f32 v0, v0, v84, v85
	v_max3_f32 v0, v0, v86, v87
	v_max3_f32 v0, v0, v88, v89
	v_max3_f32 v0, v0, v90, v91
	v_max3_f32 v0, v0, v92, v93
	v_max3_f32 v0, v0, v94, v95
	v_mov_b32_e32 v2, v0
	v_mov_b32_e32 v255, v0
	s_nop 1
	v_permlane32_swap_b32_e32 v2, v255
	s_and_b64 vcc, exec, s[38:39]
	s_waitcnt lgkmcnt(0)
	v_max3_f32 v234, v231, v2, v255
	v_sub_f32_e32 v255, v234, v231
	v_cmp_lt_f32_e64 s[98:99], 4.0, v255
	s_nop 1
	v_cndmask_b32_e64 v234, v231, v234, s[98:99]
	v_sub_f32_e32 v2, v81, v234
	v_exp_f32_e32 v14, v2
	v_sub_f32_e32 v2, v82, v234
	v_exp_f32_e32 v232, v2
	v_sub_f32_e32 v2, v83, v234
	v_exp_f32_e32 v236, v2
	v_sub_f32_e32 v2, v84, v234
	v_exp_f32_e32 v237, v2
	v_sub_f32_e32 v2, v85, v234
	v_exp_f32_e32 v238, v2
	v_sub_f32_e32 v2, v86, v234
	v_exp_f32_e32 v239, v2
	v_sub_f32_e32 v2, v87, v234
	v_exp_f32_e32 v240, v2
	v_sub_f32_e32 v2, v88, v234
	v_exp_f32_e32 v241, v2
	v_sub_f32_e32 v2, v89, v234
	v_exp_f32_e32 v242, v2
	v_sub_f32_e32 v2, v90, v234
	v_exp_f32_e32 v243, v2
	v_sub_f32_e32 v2, v91, v234
	v_exp_f32_e32 v244, v2
	v_sub_f32_e32 v2, v92, v234
	v_exp_f32_e32 v245, v2
	v_sub_f32_e32 v2, v93, v234
	v_exp_f32_e32 v246, v2
	v_sub_f32_e32 v2, v94, v234
	v_sub_f32_e32 v0, v80, v234
	v_exp_f32_e32 v247, v2
	v_sub_f32_e32 v2, v95, v234
	v_mfma_f32_32x32x16_bf16 v[80:95], v[168:171], v[112:115], 0
	v_exp_f32_e32 v0, v0
	v_exp_f32_e32 v248, v2
	v_cvt_pk_bf16_f32 v6, v0, v14
	v_cvt_pk_bf16_f32 v7, v232, v236
	v_cvt_pk_bf16_f32 v8, v237, v238
	v_cvt_pk_bf16_f32 v9, v239, v240
	v_cvt_pk_bf16_f32 v2, v241, v242
	v_mfma_f32_32x32x16_bf16 v[80:95], v[164:167], v[116:119], v[80:95]
	v_cvt_pk_bf16_f32 v3, v243, v244
	v_cvt_pk_bf16_f32 v4, v245, v246
	v_cvt_pk_bf16_f32 v5, v247, v248
	v_mfma_f32_32x32x16_bf16 v[80:95], v[10:13], v[120:123], v[80:95]
	v_mfma_f32_32x32x16_bf16 v[80:95], v[160:163], v[124:127], v[80:95]
	s_cbranch_vccnz .LBB0_326
	s_cmp_lt_i32 s3, s62
	s_cselect_b64 s[0:1], -1, 0
	s_cmp_gt_i32 s3, s55
	s_cselect_b64 s[26:27], -1, 0
	s_or_b64 s[0:1], s[0:1], s[26:27]
	s_andn2_b64 vcc, exec, s[0:1]
	s_cbranch_vccnz .LBB0_326
	s_sub_i32 s0, s33, s63
	v_add_u32_e32 v10, s0, v214
	v_cmp_lt_u32_e32 vcc, s66, v10
	v_add_u32_e32 v10, s0, v215
	s_nop 0
	v_cndmask_b32_e32 v80, v200, v80, vcc
	v_cmp_lt_u32_e32 vcc, s66, v10
	v_add_u32_e32 v10, s0, v216
	s_nop 0
	v_cndmask_b32_e32 v81, v200, v81, vcc
	v_cmp_lt_u32_e32 vcc, s66, v10
	v_add_u32_e32 v10, s0, v217
	s_nop 0
	v_cndmask_b32_e32 v82, v200, v82, vcc
	v_cmp_lt_u32_e32 vcc, s66, v10
	v_add_u32_e32 v10, s0, v218
	s_nop 0
	v_cndmask_b32_e32 v83, v200, v83, vcc
	v_cmp_lt_u32_e32 vcc, s66, v10
	v_add_u32_e32 v10, s0, v219
	s_nop 0
	v_cndmask_b32_e32 v84, v200, v84, vcc
	v_cmp_lt_u32_e32 vcc, s66, v10
	v_add_u32_e32 v10, s0, v220
	s_nop 0
	v_cndmask_b32_e32 v85, v200, v85, vcc
	v_cmp_lt_u32_e32 vcc, s66, v10
	v_add_u32_e32 v10, s0, v221
	s_nop 0
	v_cndmask_b32_e32 v86, v200, v86, vcc
	v_cmp_lt_u32_e32 vcc, s66, v10
	v_add_u32_e32 v10, s0, v222
	s_nop 0
	v_cndmask_b32_e32 v87, v200, v87, vcc
	v_cmp_lt_u32_e32 vcc, s66, v10
	v_add_u32_e32 v10, s0, v223
	s_nop 0
	v_cndmask_b32_e32 v88, v200, v88, vcc
	v_cmp_lt_u32_e32 vcc, s66, v10
	v_add_u32_e32 v10, s0, v224
	s_nop 0
	v_cndmask_b32_e32 v89, v200, v89, vcc
	v_cmp_lt_u32_e32 vcc, s66, v10
	v_add_u32_e32 v10, s0, v225
	s_nop 0
	v_cndmask_b32_e32 v90, v200, v90, vcc
	v_cmp_lt_u32_e32 vcc, s66, v10
	v_add_u32_e32 v10, s0, v226
	s_nop 0
	v_cndmask_b32_e32 v91, v200, v91, vcc
	v_cmp_lt_u32_e32 vcc, s66, v10
	v_add_u32_e32 v10, s0, v227
	s_nop 0
	v_cndmask_b32_e32 v92, v200, v92, vcc
	v_cmp_lt_u32_e32 vcc, s66, v10
	v_add_u32_e32 v10, s0, v228
	s_nop 0
	v_cndmask_b32_e32 v93, v200, v93, vcc
	v_cmp_lt_u32_e32 vcc, s66, v10
	v_add_u32_e32 v10, s0, v229
	s_nop 0
	v_cndmask_b32_e32 v94, v200, v94, vcc
	v_cmp_lt_u32_e32 vcc, s66, v10
	s_nop 1
	v_cndmask_b32_e32 v95, v200, v95, vcc

.Lrs_0:
	v_max3_f32 v0, v80, s18, v81
	v_max3_f32 v0, v0, v82, v83
	v_max3_f32 v0, v0, v84, v85
	v_max3_f32 v0, v0, v86, v87
	v_max3_f32 v0, v0, v88, v89
	v_max3_f32 v0, v0, v90, v91
	v_max3_f32 v0, v0, v92, v93
	v_max3_f32 v0, v0, v94, v95
	v_mov_b32_e32 v10, v0
	v_mov_b32_e32 v255, v0
	s_nop 1
	v_permlane32_swap_b32_e32 v10, v255
	s_waitcnt lgkmcnt(0)
	v_max3_f32 v14, v235, v10, v255
	v_sub_f32_e32 v255, v14, v235
	v_cmp_lt_f32_e64 s[98:99], 4.0, v255
	s_nop 1
	v_cndmask_b32_e64 v14, v235, v14, s[98:99]
	v_sub_f32_e32 v0, v80, v14
	v_exp_f32_e32 v11, v0
	v_sub_f32_e32 v12, v81, v14
	v_exp_f32_e32 v12, v12
	v_sub_f32_e32 v13, v82, v14
	v_exp_f32_e32 v13, v13
	v_sub_f32_e32 v80, v83, v14
	v_exp_f32_e32 v81, v80
	v_sub_f32_e32 v80, v84, v14
	v_add_f32_e32 v0, 0, v11
	v_exp_f32_e32 v82, v80
	v_sub_f32_e32 v80, v85, v14
	v_add_f32_e32 v0, v12, v0
	v_exp_f32_e32 v83, v80
	v_sub_f32_e32 v80, v86, v14
	v_add_f32_e32 v0, v13, v0
	v_exp_f32_e32 v84, v80
	v_sub_f32_e32 v80, v87, v14
	v_add_f32_e32 v0, v81, v0
	v_exp_f32_e32 v85, v80
	v_sub_f32_e32 v80, v88, v14
	v_add_f32_e32 v0, v82, v0
	v_exp_f32_e32 v86, v80
	v_sub_f32_e32 v80, v89, v14
	v_add_f32_e32 v0, v83, v0
	v_exp_f32_e32 v87, v80
	v_sub_f32_e32 v80, v90, v14
	v_add_f32_e32 v0, v84, v0
	v_exp_f32_e32 v88, v80
	v_sub_f32_e32 v80, v91, v14
	v_add_f32_e32 v0, v85, v0
	v_exp_f32_e32 v89, v80
	v_sub_f32_e32 v80, v92, v14
	v_add_f32_e32 v0, v86, v0
	v_exp_f32_e32 v90, v80
	v_sub_f32_e32 v80, v93, v14
	v_add_f32_e32 v0, v87, v0
	v_exp_f32_e32 v91, v80
	v_sub_f32_e32 v80, v94, v14
	v_add_f32_e32 v0, v88, v0
	v_exp_f32_e32 v92, v80
	v_sub_f32_e32 v80, v95, v14
	v_sub_f32_e32 v10, v235, v14
	v_add_f32_e32 v0, v89, v0
	v_exp_f32_e32 v93, v80
	v_add_f32_e32 v0, v90, v0
	v_exp_f32_e32 v10, v10
	v_add_f32_e32 v0, v91, v0
	v_add_f32_e32 v0, v92, v0
	v_add_f32_e32 v0, v93, v0
	v_fmac_f32_e32 v0, v15, v10
	s_mov_b64 vcc, s[98:99]
	s_cbranch_vccz .Lrs_1
	v_mul_f32_e32 v46, v10, v46
	v_mul_f32_e32 v47, v10, v47
	v_mul_f32_e32 v44, v10, v44
	v_mul_f32_e32 v45, v10, v45
	v_mul_f32_e32 v42, v10, v42
	v_mul_f32_e32 v43, v10, v43
	v_mul_f32_e32 v40, v10, v40
	v_mul_f32_e32 v41, v10, v41
	v_mul_f32_e32 v38, v10, v38
	v_mul_f32_e32 v39, v10, v39
	v_mul_f32_e32 v36, v10, v36
	v_mul_f32_e32 v37, v10, v37
	v_mul_f32_e32 v34, v10, v34
	v_mul_f32_e32 v35, v10, v35
	v_mul_f32_e32 v32, v10, v32
	v_mul_f32_e32 v33, v10, v33
	v_mul_f32_e32 v30, v10, v30
	v_mul_f32_e32 v31, v10, v31
	v_mul_f32_e32 v28, v10, v28
	v_mul_f32_e32 v29, v10, v29
	v_mul_f32_e32 v26, v10, v26
	v_mul_f32_e32 v27, v10, v27
	v_mul_f32_e32 v24, v10, v24
	v_mul_f32_e32 v25, v10, v25
	v_mul_f32_e32 v22, v10, v22
	v_mul_f32_e32 v23, v10, v23
	v_mul_f32_e32 v20, v10, v20
	v_mul_f32_e32 v21, v10, v21
	v_mul_f32_e32 v18, v10, v18
	v_mul_f32_e32 v19, v10, v19
	v_mul_f32_e32 v16, v10, v16
	v_mul_f32_e32 v17, v10, v17

.LBB0_344:
	s_nop 10
	v_max3_f32 v2, v80, s18, v81
	v_max3_f32 v2, v2, v82, v83
	v_max3_f32 v2, v2, v84, v85
	v_max3_f32 v2, v2, v86, v87
	v_max3_f32 v2, v2, v88, v89
	v_max3_f32 v2, v2, v90, v91
	v_max3_f32 v2, v2, v92, v93
	v_max3_f32 v2, v2, v94, v95
	v_mov_b32_e32 v3, v2
	v_mov_b32_e32 v255, v2
	s_nop 1
	v_permlane32_swap_b32_e32 v3, v255
	s_and_b64 vcc, exec, s[40:41]
	s_waitcnt lgkmcnt(0)
	v_max3_f32 v233, v234, v3, v255
	v_sub_f32_e32 v255, v233, v234
	v_cmp_lt_f32_e64 s[98:99], 4.0, v255
	s_nop 1
	v_cndmask_b32_e64 v233, v234, v233, s[98:99]
	v_sub_f32_e32 v2, v80, v233
	v_exp_f32_e32 v235, v2
	v_sub_f32_e32 v2, v81, v233
	v_exp_f32_e32 v236, v2
	v_sub_f32_e32 v2, v82, v233
	v_exp_f32_e32 v237, v2
	v_sub_f32_e32 v2, v83, v233
	v_exp_f32_e32 v238, v2
	v_sub_f32_e32 v2, v84, v233
	v_exp_f32_e32 v239, v2
	v_sub_f32_e32 v2, v85, v233
	v_exp_f32_e32 v240, v2
	v_sub_f32_e32 v2, v86, v233
	v_exp_f32_e32 v241, v2
	v_sub_f32_e32 v2, v87, v233
	v_exp_f32_e32 v242, v2
	v_sub_f32_e32 v2, v88, v233
	v_exp_f32_e32 v243, v2
	v_sub_f32_e32 v2, v89, v233
	v_exp_f32_e32 v244, v2
	v_sub_f32_e32 v2, v90, v233
	v_exp_f32_e32 v245, v2
	v_sub_f32_e32 v2, v91, v233
	v_exp_f32_e32 v246, v2
	v_sub_f32_e32 v2, v92, v233
	v_exp_f32_e32 v247, v2
	v_sub_f32_e32 v2, v93, v233
	v_exp_f32_e32 v248, v2
	v_sub_f32_e32 v2, v94, v233
	v_exp_f32_e32 v249, v2
	v_sub_f32_e32 v2, v95, v233
	v_mfma_f32_32x32x16_bf16 v[80:95], v[168:171], v[112:115], 0
	v_exp_f32_e32 v250, v2
	v_cvt_pk_bf16_f32 v6, v235, v236
	v_cvt_pk_bf16_f32 v7, v237, v238
	v_cvt_pk_bf16_f32 v8, v239, v240
	v_cvt_pk_bf16_f32 v9, v241, v242
	v_cvt_pk_bf16_f32 v2, v243, v244
	v_cvt_pk_bf16_f32 v3, v245, v246
	v_mfma_f32_32x32x16_bf16 v[80:95], v[164:167], v[116:119], v[80:95]
	v_cvt_pk_bf16_f32 v4, v247, v248
	v_cvt_pk_bf16_f32 v5, v249, v250
	v_mfma_f32_32x32x16_bf16 v[80:95], v[10:13], v[120:123], v[80:95]
	v_mfma_f32_32x32x16_bf16 v[80:95], v[160:163], v[124:127], v[80:95]
	s_cbranch_vccnz .LBB0_347
	s_cmp_lt_i32 s3, s62
	s_cselect_b64 s[0:1], -1, 0
	s_cmp_gt_i32 s3, s55
	s_cselect_b64 s[26:27], -1, 0
	s_or_b64 s[0:1], s[0:1], s[26:27]
	s_andn2_b64 vcc, exec, s[0:1]
	s_cbranch_vccnz .LBB0_347
	s_sub_i32 s0, s33, s63
	v_add_u32_e32 v10, s0, v214
	v_cmp_lt_u32_e32 vcc, s66, v10
	v_add_u32_e32 v10, s0, v215
	s_nop 0
	v_cndmask_b32_e32 v80, v200, v80, vcc
	v_cmp_lt_u32_e32 vcc, s66, v10
	v_add_u32_e32 v10, s0, v216
	s_nop 0
	v_cndmask_b32_e32 v81, v200, v81, vcc
	v_cmp_lt_u32_e32 vcc, s66, v10
	v_add_u32_e32 v10, s0, v217
	s_nop 0
	v_cndmask_b32_e32 v82, v200, v82, vcc
	v_cmp_lt_u32_e32 vcc, s66, v10
	v_add_u32_e32 v10, s0, v218
	s_nop 0
	v_cndmask_b32_e32 v83, v200, v83, vcc
	v_cmp_lt_u32_e32 vcc, s66, v10
	v_add_u32_e32 v10, s0, v219
	s_nop 0
	v_cndmask_b32_e32 v84, v200, v84, vcc
	v_cmp_lt_u32_e32 vcc, s66, v10
	v_add_u32_e32 v10, s0, v220
	s_nop 0
	v_cndmask_b32_e32 v85, v200, v85, vcc
	v_cmp_lt_u32_e32 vcc, s66, v10
	v_add_u32_e32 v10, s0, v221
	s_nop 0
	v_cndmask_b32_e32 v86, v200, v86, vcc
	v_cmp_lt_u32_e32 vcc, s66, v10
	v_add_u32_e32 v10, s0, v222
	s_nop 0
	v_cndmask_b32_e32 v87, v200, v87, vcc
	v_cmp_lt_u32_e32 vcc, s66, v10
	v_add_u32_e32 v10, s0, v223
	s_nop 0
	v_cndmask_b32_e32 v88, v200, v88, vcc
	v_cmp_lt_u32_e32 vcc, s66, v10
	v_add_u32_e32 v10, s0, v224
	s_nop 0
	v_cndmask_b32_e32 v89, v200, v89, vcc
	v_cmp_lt_u32_e32 vcc, s66, v10
	v_add_u32_e32 v10, s0, v225
	s_nop 0
	v_cndmask_b32_e32 v90, v200, v90, vcc
	v_cmp_lt_u32_e32 vcc, s66, v10
	v_add_u32_e32 v10, s0, v226
	s_nop 0
	v_cndmask_b32_e32 v91, v200, v91, vcc
	v_cmp_lt_u32_e32 vcc, s66, v10
	v_add_u32_e32 v10, s0, v227
	s_nop 0
	v_cndmask_b32_e32 v92, v200, v92, vcc
	v_cmp_lt_u32_e32 vcc, s66, v10
	v_add_u32_e32 v10, s0, v228
	s_nop 0
	v_cndmask_b32_e32 v93, v200, v93, vcc
	v_cmp_lt_u32_e32 vcc, s66, v10
	v_add_u32_e32 v10, s0, v229
	s_nop 0
	v_cndmask_b32_e32 v94, v200, v94, vcc
	v_cmp_lt_u32_e32 vcc, s66, v10
	s_nop 1
	v_cndmask_b32_e32 v95, v200, v95, vcc

.Lrs_2:
	v_max3_f32 v10, v80, s18, v81
	v_max3_f32 v10, v10, v82, v83
	v_max3_f32 v10, v10, v84, v85
	v_max3_f32 v10, v10, v86, v87
	v_max3_f32 v10, v10, v88, v89
	v_max3_f32 v10, v10, v90, v91
	v_max3_f32 v10, v10, v92, v93
	v_max3_f32 v10, v10, v94, v95
	v_mov_b32_e32 v11, v10
	v_mov_b32_e32 v255, v10
	s_nop 1
	v_permlane32_swap_b32_e32 v11, v255
	v_mov_b32_e32 v232, v160
	s_waitcnt lgkmcnt(0)
	v_max3_f32 v161, v14, v11, v255
	v_sub_f32_e32 v255, v161, v14
	v_cmp_lt_f32_e64 s[98:99], 4.0, v255
	s_nop 1
	v_cndmask_b32_e64 v161, v14, v161, s[98:99]
	v_sub_f32_e32 v11, v80, v161
	v_exp_f32_e32 v11, v11
	v_sub_f32_e32 v13, v81, v161
	v_sub_f32_e32 v10, v14, v161
	v_exp_f32_e32 v13, v13
	v_sub_f32_e32 v14, v82, v161
	v_exp_f32_e32 v14, v14
	v_sub_f32_e32 v80, v83, v161
	v_exp_f32_e32 v81, v80
	v_sub_f32_e32 v80, v84, v161
	v_add_f32_e32 v12, 0, v11
	v_exp_f32_e32 v82, v80
	v_sub_f32_e32 v80, v85, v161
	v_add_f32_e32 v12, v13, v12
	v_exp_f32_e32 v83, v80
	v_sub_f32_e32 v80, v86, v161
	v_add_f32_e32 v12, v14, v12
	v_exp_f32_e32 v85, v80
	v_sub_f32_e32 v80, v87, v161
	v_add_f32_e32 v12, v81, v12
	v_exp_f32_e32 v86, v80
	v_sub_f32_e32 v80, v88, v161
	v_add_f32_e32 v12, v82, v12
	v_exp_f32_e32 v87, v80
	v_sub_f32_e32 v80, v89, v161
	v_add_f32_e32 v12, v83, v12
	v_exp_f32_e32 v88, v80
	v_sub_f32_e32 v80, v90, v161
	v_add_f32_e32 v12, v85, v12
	v_exp_f32_e32 v89, v80
	v_sub_f32_e32 v80, v91, v161
	v_add_f32_e32 v12, v86, v12
	v_exp_f32_e32 v90, v80
	v_sub_f32_e32 v80, v92, v161
	v_add_f32_e32 v12, v87, v12
	v_exp_f32_e32 v91, v80
	v_sub_f32_e32 v80, v93, v161
	v_add_f32_e32 v12, v88, v12
	v_exp_f32_e32 v92, v80
	v_sub_f32_e32 v80, v94, v161
	v_add_f32_e32 v12, v89, v12
	v_exp_f32_e32 v93, v80
	v_sub_f32_e32 v80, v95, v161
	v_add_f32_e32 v12, v90, v12
	v_exp_f32_e32 v94, v80
	v_add_f32_e32 v12, v91, v12
	v_exp_f32_e32 v10, v10
	v_add_f32_e32 v12, v92, v12
	v_add_f32_e32 v12, v93, v12
	v_add_f32_e32 v84, v94, v12
	v_fmac_f32_e32 v84, v0, v10
	v_add_u32_e32 v0, 0x3800, v230
	s_mov_b64 vcc, s[98:99]
	s_cbranch_vccz .Lrs_3
	v_mul_f32_e32 v46, v10, v46
	v_mul_f32_e32 v47, v10, v47
	v_mul_f32_e32 v44, v10, v44
	v_mul_f32_e32 v45, v10, v45
	v_mul_f32_e32 v42, v10, v42
	v_mul_f32_e32 v43, v10, v43
	v_mul_f32_e32 v40, v10, v40
	v_mul_f32_e32 v41, v10, v41
	v_mul_f32_e32 v38, v10, v38
	v_mul_f32_e32 v39, v10, v39
	v_mul_f32_e32 v36, v10, v36
	v_mul_f32_e32 v37, v10, v37
	v_mul_f32_e32 v34, v10, v34
	v_mul_f32_e32 v35, v10, v35
	v_mul_f32_e32 v32, v10, v32
	v_mul_f32_e32 v33, v10, v33
	v_mul_f32_e32 v30, v10, v30
	v_mul_f32_e32 v31, v10, v31
	v_mul_f32_e32 v28, v10, v28
	v_mul_f32_e32 v29, v10, v29
	v_mul_f32_e32 v26, v10, v26
	v_mul_f32_e32 v27, v10, v27
	v_mul_f32_e32 v24, v10, v24
	v_mul_f32_e32 v25, v10, v25
	v_mul_f32_e32 v22, v10, v22
	v_mul_f32_e32 v23, v10, v23
	v_mul_f32_e32 v20, v10, v20
	v_mul_f32_e32 v21, v10, v21
	v_mul_f32_e32 v18, v10, v18
	v_mul_f32_e32 v19, v10, v19
	v_mul_f32_e32 v16, v10, v16
	v_mul_f32_e32 v17, v10, v17

.LBB0_362:
	s_nop 10
	v_max3_f32 v2, v80, s18, v81
	v_max3_f32 v2, v2, v82, v83
	v_max3_f32 v2, v2, v84, v85
	v_max3_f32 v2, v2, v86, v87
	v_max3_f32 v2, v2, v88, v89
	v_max3_f32 v2, v2, v90, v91
	v_max3_f32 v2, v2, v92, v93
	v_max3_f32 v2, v2, v94, v95
	v_mov_b32_e32 v3, v2
	v_mov_b32_e32 v255, v2
	s_nop 1
	v_permlane32_swap_b32_e32 v3, v255
	s_and_b64 vcc, exec, s[40:41]
	s_waitcnt lgkmcnt(0)
	v_max3_f32 v234, v233, v3, v255
	v_sub_f32_e32 v255, v234, v233
	v_cmp_lt_f32_e64 s[98:99], 4.0, v255
	s_nop 1
	v_cndmask_b32_e64 v234, v233, v234, s[98:99]
	v_sub_f32_e32 v2, v80, v234
	v_exp_f32_e32 v235, v2
	v_sub_f32_e32 v2, v81, v234
	v_exp_f32_e32 v236, v2
	v_sub_f32_e32 v2, v82, v234
	v_exp_f32_e32 v237, v2
	v_sub_f32_e32 v2, v83, v234
	v_exp_f32_e32 v238, v2
	v_sub_f32_e32 v2, v84, v234
	v_exp_f32_e32 v239, v2
	v_sub_f32_e32 v2, v85, v234
	v_exp_f32_e32 v240, v2
	v_sub_f32_e32 v2, v86, v234
	v_exp_f32_e32 v241, v2
	v_sub_f32_e32 v2, v87, v234
	v_exp_f32_e32 v242, v2
	v_sub_f32_e32 v2, v88, v234
	v_exp_f32_e32 v243, v2
	v_sub_f32_e32 v2, v89, v234
	v_exp_f32_e32 v244, v2
	v_sub_f32_e32 v2, v90, v234
	v_exp_f32_e32 v245, v2
	v_sub_f32_e32 v2, v91, v234
	v_exp_f32_e32 v246, v2
	v_sub_f32_e32 v2, v92, v234
	v_exp_f32_e32 v247, v2
	v_sub_f32_e32 v2, v93, v234
	v_exp_f32_e32 v248, v2
	v_sub_f32_e32 v2, v94, v234
	v_exp_f32_e32 v249, v2
	v_sub_f32_e32 v2, v95, v234
	v_mfma_f32_32x32x16_bf16 v[80:95], v[168:171], v[112:115], 0
	v_exp_f32_e32 v250, v2
	v_cvt_pk_bf16_f32 v6, v235, v236
	v_cvt_pk_bf16_f32 v7, v237, v238
	v_cvt_pk_bf16_f32 v8, v239, v240
	v_cvt_pk_bf16_f32 v9, v241, v242
	v_cvt_pk_bf16_f32 v2, v243, v244
	v_cvt_pk_bf16_f32 v3, v245, v246
	v_mfma_f32_32x32x16_bf16 v[80:95], v[164:167], v[116:119], v[80:95]
	v_cvt_pk_bf16_f32 v4, v247, v248
	v_cvt_pk_bf16_f32 v5, v249, v250
	v_mfma_f32_32x32x16_bf16 v[80:95], v[10:13], v[120:123], v[80:95]
	v_mfma_f32_32x32x16_bf16 v[80:95], v[160:163], v[124:127], v[80:95]
	s_cbranch_vccnz .LBB0_365
	s_cmp_lt_i32 s3, s62
	s_cselect_b64 s[0:1], -1, 0
	s_cmp_gt_i32 s3, s55
	s_cselect_b64 s[26:27], -1, 0
	s_or_b64 s[0:1], s[0:1], s[26:27]
	s_andn2_b64 vcc, exec, s[0:1]
	s_cbranch_vccnz .LBB0_365
	s_sub_i32 s0, s33, s63
	v_add_u32_e32 v10, s0, v214
	v_cmp_lt_u32_e32 vcc, s66, v10
	v_add_u32_e32 v10, s0, v215
	s_nop 0
	v_cndmask_b32_e32 v80, v200, v80, vcc
	v_cmp_lt_u32_e32 vcc, s66, v10
	v_add_u32_e32 v10, s0, v216
	s_nop 0
	v_cndmask_b32_e32 v81, v200, v81, vcc
	v_cmp_lt_u32_e32 vcc, s66, v10
	v_add_u32_e32 v10, s0, v217
	s_nop 0
	v_cndmask_b32_e32 v82, v200, v82, vcc
	v_cmp_lt_u32_e32 vcc, s66, v10
	v_add_u32_e32 v10, s0, v218
	s_nop 0
	v_cndmask_b32_e32 v83, v200, v83, vcc
	v_cmp_lt_u32_e32 vcc, s66, v10
	v_add_u32_e32 v10, s0, v219
	s_nop 0
	v_cndmask_b32_e32 v84, v200, v84, vcc
	v_cmp_lt_u32_e32 vcc, s66, v10
	v_add_u32_e32 v10, s0, v220
	s_nop 0
	v_cndmask_b32_e32 v85, v200, v85, vcc
	v_cmp_lt_u32_e32 vcc, s66, v10
	v_add_u32_e32 v10, s0, v221
	s_nop 0
	v_cndmask_b32_e32 v86, v200, v86, vcc
	v_cmp_lt_u32_e32 vcc, s66, v10
	v_add_u32_e32 v10, s0, v222
	s_nop 0
	v_cndmask_b32_e32 v87, v200, v87, vcc
	v_cmp_lt_u32_e32 vcc, s66, v10
	v_add_u32_e32 v10, s0, v223
	s_nop 0
	v_cndmask_b32_e32 v88, v200, v88, vcc
	v_cmp_lt_u32_e32 vcc, s66, v10
	v_add_u32_e32 v10, s0, v224
	s_nop 0
	v_cndmask_b32_e32 v89, v200, v89, vcc
	v_cmp_lt_u32_e32 vcc, s66, v10
	v_add_u32_e32 v10, s0, v225
	s_nop 0
	v_cndmask_b32_e32 v90, v200, v90, vcc
	v_cmp_lt_u32_e32 vcc, s66, v10
	v_add_u32_e32 v10, s0, v226
	s_nop 0
	v_cndmask_b32_e32 v91, v200, v91, vcc
	v_cmp_lt_u32_e32 vcc, s66, v10
	v_add_u32_e32 v10, s0, v227
	s_nop 0
	v_cndmask_b32_e32 v92, v200, v92, vcc
	v_cmp_lt_u32_e32 vcc, s66, v10
	v_add_u32_e32 v10, s0, v228
	s_nop 0
	v_cndmask_b32_e32 v93, v200, v93, vcc
	v_cmp_lt_u32_e32 vcc, s66, v10
	v_add_u32_e32 v10, s0, v229
	s_nop 0
	v_cndmask_b32_e32 v94, v200, v94, vcc
	v_cmp_lt_u32_e32 vcc, s66, v10
	s_nop 1
	v_cndmask_b32_e32 v95, v200, v95, vcc

.Lrs_4:
	v_max3_f32 v10, v80, s18, v81
	v_max3_f32 v10, v10, v82, v83
	v_max3_f32 v10, v10, v84, v85
	v_max3_f32 v10, v10, v86, v87
	v_max3_f32 v10, v10, v88, v89
	v_max3_f32 v10, v10, v90, v91
	v_max3_f32 v10, v10, v92, v93
	v_max3_f32 v10, v10, v94, v95
	v_mov_b32_e32 v11, v10
	v_mov_b32_e32 v255, v10
	s_nop 1
	v_permlane32_swap_b32_e32 v11, v255
	v_mov_b32_e32 v232, v160
	s_waitcnt lgkmcnt(0)
	v_max3_f32 v161, v14, v11, v255
	v_sub_f32_e32 v255, v161, v14
	v_cmp_lt_f32_e64 s[98:99], 4.0, v255
	s_nop 1
	v_cndmask_b32_e64 v161, v14, v161, s[98:99]
	v_sub_f32_e32 v11, v80, v161
	v_exp_f32_e32 v11, v11
	v_sub_f32_e32 v13, v81, v161
	v_sub_f32_e32 v10, v14, v161
	v_exp_f32_e32 v13, v13
	v_sub_f32_e32 v14, v82, v161
	v_exp_f32_e32 v14, v14
	v_sub_f32_e32 v80, v83, v161
	v_exp_f32_e32 v81, v80
	v_sub_f32_e32 v80, v84, v161
	v_add_f32_e32 v12, 0, v11
	v_exp_f32_e32 v82, v80
	v_sub_f32_e32 v80, v85, v161
	v_add_f32_e32 v12, v13, v12
	v_exp_f32_e32 v83, v80
	v_sub_f32_e32 v80, v86, v161
	v_add_f32_e32 v12, v14, v12
	v_exp_f32_e32 v85, v80
	v_sub_f32_e32 v80, v87, v161
	v_add_f32_e32 v12, v81, v12
	v_exp_f32_e32 v86, v80
	v_sub_f32_e32 v80, v88, v161
	v_add_f32_e32 v12, v82, v12
	v_exp_f32_e32 v87, v80
	v_sub_f32_e32 v80, v89, v161
	v_add_f32_e32 v12, v83, v12
	v_exp_f32_e32 v88, v80
	v_sub_f32_e32 v80, v90, v161
	v_add_f32_e32 v12, v85, v12
	v_exp_f32_e32 v89, v80
	v_sub_f32_e32 v80, v91, v161
	v_add_f32_e32 v12, v86, v12
	v_exp_f32_e32 v90, v80
	v_sub_f32_e32 v80, v92, v161
	v_add_f32_e32 v12, v87, v12
	v_exp_f32_e32 v91, v80
	v_sub_f32_e32 v80, v93, v161
	v_add_f32_e32 v12, v88, v12
	v_exp_f32_e32 v92, v80
	v_sub_f32_e32 v80, v94, v161
	v_add_f32_e32 v12, v89, v12
	v_exp_f32_e32 v93, v80
	v_sub_f32_e32 v80, v95, v161
	v_add_f32_e32 v12, v90, v12
	v_exp_f32_e32 v94, v80
	v_add_f32_e32 v12, v91, v12
	v_exp_f32_e32 v10, v10
	v_add_f32_e32 v12, v92, v12
	v_add_f32_e32 v12, v93, v12
	v_add_f32_e32 v84, v94, v12
	v_fmac_f32_e32 v84, v0, v10
	s_mov_b64 vcc, s[98:99]
	s_cbranch_vccz .Lrs_5
	v_mul_f32_e32 v46, v10, v46
	v_mul_f32_e32 v47, v10, v47
	v_mul_f32_e32 v44, v10, v44
	v_mul_f32_e32 v45, v10, v45
	v_mul_f32_e32 v42, v10, v42
	v_mul_f32_e32 v43, v10, v43
	v_mul_f32_e32 v40, v10, v40
	v_mul_f32_e32 v41, v10, v41
	v_mul_f32_e32 v38, v10, v38
	v_mul_f32_e32 v39, v10, v39
	v_mul_f32_e32 v36, v10, v36
	v_mul_f32_e32 v37, v10, v37
	v_mul_f32_e32 v34, v10, v34
	v_mul_f32_e32 v35, v10, v35
	v_mul_f32_e32 v32, v10, v32
	v_mul_f32_e32 v33, v10, v33
	v_mul_f32_e32 v30, v10, v30
	v_mul_f32_e32 v31, v10, v31
	v_mul_f32_e32 v28, v10, v28
	v_mul_f32_e32 v29, v10, v29
	v_mul_f32_e32 v26, v10, v26
	v_mul_f32_e32 v27, v10, v27
	v_mul_f32_e32 v24, v10, v24
	v_mul_f32_e32 v25, v10, v25
	v_mul_f32_e32 v22, v10, v22
	v_mul_f32_e32 v23, v10, v23
	v_mul_f32_e32 v20, v10, v20
	v_mul_f32_e32 v21, v10, v21
	v_mul_f32_e32 v18, v10, v18
	v_mul_f32_e32 v19, v10, v19
	v_mul_f32_e32 v16, v10, v16
	v_mul_f32_e32 v17, v10, v17

.LBB0_378:
	s_nop 10
	v_max3_f32 v2, v80, s18, v81
	v_max3_f32 v2, v2, v82, v83
	v_max3_f32 v2, v2, v84, v85
	v_max3_f32 v2, v2, v86, v87
	v_max3_f32 v2, v2, v88, v89
	v_max3_f32 v2, v2, v90, v91
	v_max3_f32 v2, v2, v92, v93
	v_max3_f32 v2, v2, v94, v95
	v_mov_b32_e32 v3, v2
	v_mov_b32_e32 v255, v2
	s_nop 1
	v_permlane32_swap_b32_e32 v3, v255
	s_and_b64 vcc, exec, s[38:39]
	s_waitcnt lgkmcnt(0)
	v_max3_f32 v231, v234, v3, v255
	v_sub_f32_e32 v255, v231, v234
	v_cmp_lt_f32_e64 s[98:99], 4.0, v255
	s_nop 1
	v_cndmask_b32_e64 v231, v234, v231, s[98:99]
	v_sub_f32_e32 v2, v80, v231
	v_exp_f32_e32 v15, v2
	v_sub_f32_e32 v2, v81, v231
	v_exp_f32_e32 v233, v2
	v_sub_f32_e32 v2, v82, v231
	v_exp_f32_e32 v235, v2
	v_sub_f32_e32 v2, v83, v231
	v_exp_f32_e32 v236, v2
	v_sub_f32_e32 v2, v84, v231
	v_exp_f32_e32 v237, v2
	v_sub_f32_e32 v2, v85, v231
	v_exp_f32_e32 v238, v2
	v_sub_f32_e32 v2, v86, v231
	v_exp_f32_e32 v239, v2
	v_sub_f32_e32 v2, v87, v231
	v_exp_f32_e32 v240, v2
	v_sub_f32_e32 v2, v88, v231
	v_exp_f32_e32 v241, v2
	v_sub_f32_e32 v2, v89, v231
	v_exp_f32_e32 v242, v2
	v_sub_f32_e32 v2, v90, v231
	v_exp_f32_e32 v243, v2
	v_sub_f32_e32 v2, v91, v231
	v_exp_f32_e32 v244, v2
	v_sub_f32_e32 v2, v92, v231
	v_exp_f32_e32 v245, v2
	v_sub_f32_e32 v2, v93, v231
	v_exp_f32_e32 v246, v2
	v_sub_f32_e32 v2, v94, v231
	v_exp_f32_e32 v247, v2
	v_sub_f32_e32 v2, v95, v231
	v_mfma_f32_32x32x16_bf16 v[80:95], v[168:171], v[112:115], 0
	v_exp_f32_e32 v248, v2
	v_cvt_pk_bf16_f32 v6, v15, v233
	v_cvt_pk_bf16_f32 v7, v235, v236
	v_cvt_pk_bf16_f32 v8, v237, v238
	v_cvt_pk_bf16_f32 v9, v239, v240
	v_cvt_pk_bf16_f32 v2, v241, v242
	v_cvt_pk_bf16_f32 v3, v243, v244
	v_mfma_f32_32x32x16_bf16 v[80:95], v[164:167], v[116:119], v[80:95]
	v_cvt_pk_bf16_f32 v4, v245, v246
	v_cvt_pk_bf16_f32 v5, v247, v248
	v_mfma_f32_32x32x16_bf16 v[80:95], v[10:13], v[120:123], v[80:95]
	v_mfma_f32_32x32x16_bf16 v[80:95], v[160:163], v[124:127], v[80:95]
	s_cbranch_vccnz .LBB0_381
	s_cmp_lt_i32 s3, s62
	s_cselect_b64 s[0:1], -1, 0
	s_cmp_gt_i32 s3, s55
	s_cselect_b64 s[26:27], -1, 0
	s_or_b64 s[0:1], s[0:1], s[26:27]
	s_andn2_b64 vcc, exec, s[0:1]
	s_cbranch_vccnz .LBB0_381
	s_sub_i32 s0, s2, s63
	v_add_u32_e32 v10, s0, v214
	v_cmp_lt_u32_e32 vcc, s66, v10
	v_add_u32_e32 v10, s0, v215
	s_nop 0
	v_cndmask_b32_e32 v80, v200, v80, vcc
	v_cmp_lt_u32_e32 vcc, s66, v10
	v_add_u32_e32 v10, s0, v216
	s_nop 0
	v_cndmask_b32_e32 v81, v200, v81, vcc
	v_cmp_lt_u32_e32 vcc, s66, v10
	v_add_u32_e32 v10, s0, v217
	s_nop 0
	v_cndmask_b32_e32 v82, v200, v82, vcc
	v_cmp_lt_u32_e32 vcc, s66, v10
	v_add_u32_e32 v10, s0, v218
	s_nop 0
	v_cndmask_b32_e32 v83, v200, v83, vcc
	v_cmp_lt_u32_e32 vcc, s66, v10
	v_add_u32_e32 v10, s0, v219
	s_nop 0
	v_cndmask_b32_e32 v84, v200, v84, vcc
	v_cmp_lt_u32_e32 vcc, s66, v10
	v_add_u32_e32 v10, s0, v220
	s_nop 0
	v_cndmask_b32_e32 v85, v200, v85, vcc
	v_cmp_lt_u32_e32 vcc, s66, v10
	v_add_u32_e32 v10, s0, v221
	s_nop 0
	v_cndmask_b32_e32 v86, v200, v86, vcc
	v_cmp_lt_u32_e32 vcc, s66, v10
	v_add_u32_e32 v10, s0, v222
	s_nop 0
	v_cndmask_b32_e32 v87, v200, v87, vcc
	v_cmp_lt_u32_e32 vcc, s66, v10
	v_add_u32_e32 v10, s0, v223
	s_nop 0
	v_cndmask_b32_e32 v88, v200, v88, vcc
	v_cmp_lt_u32_e32 vcc, s66, v10
	v_add_u32_e32 v10, s0, v224
	s_nop 0
	v_cndmask_b32_e32 v89, v200, v89, vcc
	v_cmp_lt_u32_e32 vcc, s66, v10
	v_add_u32_e32 v10, s0, v225
	s_nop 0
	v_cndmask_b32_e32 v90, v200, v90, vcc
	v_cmp_lt_u32_e32 vcc, s66, v10
	v_add_u32_e32 v10, s0, v226
	s_nop 0
	v_cndmask_b32_e32 v91, v200, v91, vcc
	v_cmp_lt_u32_e32 vcc, s66, v10
	v_add_u32_e32 v10, s0, v227
	s_nop 0
	v_cndmask_b32_e32 v92, v200, v92, vcc
	v_cmp_lt_u32_e32 vcc, s66, v10
	v_add_u32_e32 v10, s0, v228
	s_nop 0
	v_cndmask_b32_e32 v93, v200, v93, vcc
	v_cmp_lt_u32_e32 vcc, s66, v10
	v_add_u32_e32 v10, s0, v229
	s_nop 0
	v_cndmask_b32_e32 v94, v200, v94, vcc
	v_cmp_lt_u32_e32 vcc, s66, v10
	s_nop 1
	v_cndmask_b32_e32 v95, v200, v95, vcc

.Lrs_6:
	v_max3_f32 v10, v80, s18, v81
	v_max3_f32 v10, v10, v82, v83
	v_max3_f32 v10, v10, v84, v85
	v_max3_f32 v10, v10, v86, v87
	v_max3_f32 v10, v10, v88, v89
	v_max3_f32 v10, v10, v90, v91
	v_max3_f32 v10, v10, v92, v93
	v_max3_f32 v10, v10, v94, v95
	v_mov_b32_e32 v11, v10
	v_mov_b32_e32 v255, v10
	s_nop 1
	v_permlane32_swap_b32_e32 v11, v255
	s_waitcnt lgkmcnt(0)
	v_max3_f32 v235, v14, v11, v255
	v_sub_f32_e32 v255, v235, v14
	v_cmp_lt_f32_e64 s[98:99], 4.0, v255
	s_nop 1
	v_cndmask_b32_e64 v235, v14, v235, s[98:99]
	v_sub_f32_e32 v11, v80, v235
	v_exp_f32_e32 v11, v11
	v_sub_f32_e32 v13, v81, v235
	v_sub_f32_e32 v10, v14, v235
	v_exp_f32_e32 v13, v13
	v_sub_f32_e32 v14, v82, v235
	v_exp_f32_e32 v14, v14
	v_sub_f32_e32 v15, v83, v235
	v_exp_f32_e32 v81, v15
	v_sub_f32_e32 v15, v84, v235
	v_add_f32_e32 v12, 0, v11
	v_exp_f32_e32 v82, v15
	v_sub_f32_e32 v15, v85, v235
	v_add_f32_e32 v12, v13, v12
	v_exp_f32_e32 v83, v15
	v_sub_f32_e32 v15, v86, v235
	v_add_f32_e32 v12, v14, v12
	v_exp_f32_e32 v84, v15
	v_sub_f32_e32 v15, v87, v235
	v_add_f32_e32 v12, v81, v12
	v_exp_f32_e32 v85, v15
	v_sub_f32_e32 v15, v88, v235
	v_add_f32_e32 v12, v82, v12
	v_exp_f32_e32 v86, v15
	v_sub_f32_e32 v15, v89, v235
	v_add_f32_e32 v12, v83, v12
	v_exp_f32_e32 v87, v15
	v_sub_f32_e32 v15, v90, v235
	v_add_f32_e32 v12, v84, v12
	v_exp_f32_e32 v88, v15
	v_sub_f32_e32 v15, v91, v235
	v_add_f32_e32 v12, v85, v12
	v_exp_f32_e32 v89, v15
	v_sub_f32_e32 v15, v92, v235
	v_add_f32_e32 v12, v86, v12
	v_exp_f32_e32 v90, v15
	v_sub_f32_e32 v15, v93, v235
	v_add_f32_e32 v12, v87, v12
	v_exp_f32_e32 v91, v15
	v_sub_f32_e32 v15, v94, v235
	v_add_f32_e32 v12, v88, v12
	v_exp_f32_e32 v92, v15
	v_sub_f32_e32 v15, v95, v235
	v_add_f32_e32 v12, v89, v12
	v_exp_f32_e32 v93, v15
	v_add_f32_e32 v12, v90, v12
	v_exp_f32_e32 v10, v10
	v_add_f32_e32 v12, v91, v12
	v_add_f32_e32 v12, v92, v12
	v_add_f32_e32 v15, v93, v12
	v_fmac_f32_e32 v15, v0, v10
	v_add_u32_e32 v0, 0x3800, v230
	s_mov_b64 vcc, s[98:99]
	s_cbranch_vccz .Lrs_7
	v_mul_f32_e32 v46, v10, v46
	v_mul_f32_e32 v47, v10, v47
	v_mul_f32_e32 v44, v10, v44
	v_mul_f32_e32 v45, v10, v45
	v_mul_f32_e32 v42, v10, v42
	v_mul_f32_e32 v43, v10, v43
	v_mul_f32_e32 v40, v10, v40
	v_mul_f32_e32 v41, v10, v41
	v_mul_f32_e32 v38, v10, v38
	v_mul_f32_e32 v39, v10, v39
	v_mul_f32_e32 v36, v10, v36
	v_mul_f32_e32 v37, v10, v37
	v_mul_f32_e32 v34, v10, v34
	v_mul_f32_e32 v35, v10, v35
	v_mul_f32_e32 v32, v10, v32
	v_mul_f32_e32 v33, v10, v33
	v_mul_f32_e32 v30, v10, v30
	v_mul_f32_e32 v31, v10, v31
	v_mul_f32_e32 v28, v10, v28
	v_mul_f32_e32 v29, v10, v29
	v_mul_f32_e32 v26, v10, v26
	v_mul_f32_e32 v27, v10, v27
	v_mul_f32_e32 v24, v10, v24
	v_mul_f32_e32 v25, v10, v25
	v_mul_f32_e32 v22, v10, v22
	v_mul_f32_e32 v23, v10, v23
	v_mul_f32_e32 v20, v10, v20
	v_mul_f32_e32 v21, v10, v21
	v_mul_f32_e32 v18, v10, v18
	v_mul_f32_e32 v19, v10, v19
	v_mul_f32_e32 v16, v10, v16
	v_mul_f32_e32 v17, v10, v17
